# adaLN modulation GEMV (phase 0): weight-row loads software-pipelined one 4-row step ahead instead of two HBM round trips per step
# speedup vs baseline: 1.0150x; 1.0058x over previous
; DI void phase_prep(const Params& P, char* smem) {
;     ...
;       const int nl = tid & 63, ks = tid >> 6;
;       float acc[17];
; #pragma unroll
;       for (int r = 0; r < 17; ++r) acc[r] = 0.f;
;       const float* wp = P.w_mod + ((size_t)layer * 1024 + ks * 128) * 3072 + n0 + nl;
;       for (int k = 0; k < 128; ++k) {
;         const float wv = wp[(size_t)k * 3072];
; #pragma unroll
;         for (int r = 0; r < 17; ++r) acc[r] += s[r * 1024 + ks * 128 + k] * wv;
;       }
.LBB0_839:
	s_or_b64 exec, exec, s[0:1]
	s_mul_hi_i32 s0, s74, 0x2aaaaaab
	s_lshr_b32 s1, s0, 31
	s_ashr_i32 s44, s0, 3
	s_add_i32 s44, s44, s1
	s_mul_i32 s0, s44, 48
	s_sub_i32 s0, s74, s0
	s_lshl_b32 s0, s0, 6
	s_ashr_i32 s1, s0, 31
	s_mul_i32 s25, s44, 0xc00000
	s_lshl_b64 s[2:3], s[0:1], 2
	s_mul_hi_i32 s24, s44, 0xc00000
	s_add_u32 s2, s25, s2
	s_addc_u32 s3, s24, s3
	v_mov_b32_e32 v60, 0
	v_lshl_add_u64 v[42:43], v[40:41], 0, s[2:3]
	s_mov_b32 s1, 0
	v_mov_b32_e32 v61, v60
	v_mov_b32_e32 v64, v60
	v_mov_b32_e32 v65, v60
	v_mov_b32_e32 v66, v60
	v_mov_b32_e32 v67, v60
	v_mov_b32_e32 v68, v60
	v_mov_b32_e32 v69, v60
	v_mov_b32_e32 v70, v60
	v_mov_b32_e32 v71, v60
	v_mov_b32_e32 v72, v60
	v_mov_b32_e32 v73, v60
	v_mov_b32_e32 v74, v60
	v_mov_b32_e32 v75, v60
	v_mov_b32_e32 v76, v60
	v_mov_b32_e32 v77, v60
	v_mov_b32_e32 v86, v60
	s_waitcnt vmcnt(0) lgkmcnt(0)
	s_barrier
	s_mov_b32 s2, 0xffff7000
	v_add_co_u32_e32 v108, vcc, s2, v42
	s_nop 1
	v_addc_co_u32_e32 v109, vcc, -1, v43, vcc
	global_load_dword v104, v[108:109], off
	s_movk_i32 s2, 0xa000
	v_add_co_u32_e32 v108, vcc, s2, v42
	s_nop 1
	v_addc_co_u32_e32 v109, vcc, -1, v43, vcc
	global_load_dword v105, v[108:109], off
	s_movk_i32 s2, 0xd000
	v_add_co_u32_e32 v108, vcc, s2, v42
	s_nop 1
	v_addc_co_u32_e32 v109, vcc, -1, v43, vcc
	global_load_dword v106, v[108:109], off
	global_load_dword v107, v[42:43], off
.LBB0_840:
	s_waitcnt vmcnt(0)
	v_mov_b32_e32 v112, v104
	v_mov_b32_e32 v114, v105
	v_mov_b32_e32 v116, v106
	v_mov_b32_e32 v118, v107
	s_cmpk_eq_i32 s1, 0x1f0
	s_cbranch_scc1 .Lprep_nopf
	s_mov_b64 s[2:3], 0x3000
	v_lshl_add_u64 v[108:109], v[42:43], 0, s[2:3]
	global_load_dword v104, v[108:109], off
	s_mov_b64 s[2:3], 0x6000
	v_lshl_add_u64 v[108:109], v[42:43], 0, s[2:3]
	global_load_dword v105, v[108:109], off
	s_mov_b64 s[2:3], 0x9000
	v_lshl_add_u64 v[108:109], v[42:43], 0, s[2:3]
	global_load_dword v106, v[108:109], off
	s_mov_b64 s[2:3], 0xc000
	v_lshl_add_u64 v[108:109], v[42:43], 0, s[2:3]
	global_load_dword v107, v[108:109], off
; DI void phase_prep(const Params& P, char* smem) {
;     ...
;       for (int k = 0; k < 128; ++k) {
;         const float wv = wp[(size_t)k * 3072];
; #pragma unroll
;         for (int r = 0; r < 17; ++r) acc[r] += s[r * 1024 + ks * 128 + k] * wv;
;       }
; #pragma unroll
;       for (int r = 0; r < 17; ++r) red[(ks * 17 + r) * 64 + nl] = acc[r];
;       __syncthreads();
;       for (int o = tid; o < 17 * 64; o += 512) {
;         const int r = o >> 6, n = o & 63;
;         float v = P.b_mod[layer * 3072 + n0 + n];
; #pragma unroll
;         for (int k2 = 0; k2 < 8; ++k2) v += red[(k2 * 17 + r) * 64 + n];
;         mods[(layer * 17 + r) * 3072 + n0 + n] = v;
.Lprep_nopf:
	v_add_u32_e32 v87, s1, v81
	ds_read_b128 v[20:23], v87
	ds_read_b128 v[0:3], v87 offset:4096
	ds_read_b128 v[24:27], v87 offset:8192
	ds_read_b128 v[4:7], v87 offset:12288
	ds_read_b128 v[28:31], v87 offset:16384
	ds_read_b128 v[8:11], v87 offset:20480
	ds_read_b128 v[32:35], v87 offset:24576
	ds_read_b128 v[12:15], v87 offset:28672
	ds_read_b128 v[44:47], v87 offset:32768
	ds_read_b128 v[16:19], v87 offset:36864
	s_waitcnt lgkmcnt(9)
	v_mov_b32_e32 v62, v20
	s_waitcnt lgkmcnt(8)
	v_mov_b32_e32 v63, v0
	s_waitcnt lgkmcnt(7)
	v_mov_b32_e32 v88, v24
	s_waitcnt lgkmcnt(6)
	v_mov_b32_e32 v89, v4
	v_mov_b32_e32 v0, v21
	v_mov_b32_e32 v52, v22
	v_mov_b32_e32 v53, v2
	v_mov_b32_e32 v2, v23
	v_mov_b32_e32 v4, v25
	v_mov_b32_e32 v54, v26
	v_mov_b32_e32 v55, v6
	v_mov_b32_e32 v6, v27
	ds_read_b128 v[24:27], v87 offset:40960
	ds_read_b128 v[20:23], v87 offset:45056
	s_waitcnt lgkmcnt(7)
	v_mov_b32_e32 v90, v28
	s_waitcnt lgkmcnt(6)
	v_mov_b32_e32 v91, v8
	v_mov_b32_e32 v8, v29
	v_mov_b32_e32 v56, v30
	v_mov_b32_e32 v57, v10
	v_mov_b32_e32 v10, v31
	s_waitcnt lgkmcnt(3)
	v_mov_b32_e32 v94, v44
	s_waitcnt lgkmcnt(2)
	v_mov_b32_e32 v95, v16
	v_mov_b32_e32 v16, v45
	v_mov_b32_e32 v44, v46
	v_mov_b32_e32 v45, v18
	v_mov_b32_e32 v18, v47
	s_waitcnt lgkmcnt(1)
	v_mov_b32_e32 v96, v24
	s_waitcnt lgkmcnt(0)
	v_mov_b32_e32 v97, v20
	v_mov_b32_e32 v20, v25
	v_mov_b32_e32 v46, v26
	v_mov_b32_e32 v47, v22
	v_mov_b32_e32 v22, v27
	ds_read_b128 v[28:31], v87 offset:49152
	ds_read_b128 v[24:27], v87 offset:53248
	v_mov_b32_e32 v92, v32
	v_mov_b32_e32 v93, v12
	v_mov_b32_e32 v12, v33
	v_mov_b32_e32 v58, v34
	v_mov_b32_e32 v59, v14
	v_mov_b32_e32 v14, v35
	s_waitcnt lgkmcnt(1)
	v_mov_b32_e32 v98, v28
	s_waitcnt lgkmcnt(0)
	v_mov_b32_e32 v99, v24
	v_mov_b32_e32 v24, v29
	v_mov_b32_e32 v48, v30
	v_mov_b32_e32 v49, v26
	v_mov_b32_e32 v26, v31
	ds_read_b128 v[32:35], v87 offset:57344
	ds_read_b128 v[28:31], v87 offset:61440
	s_mov_b32 s2, 0xffff7000
	s_add_i32 s1, s1, 16
	s_cmpk_eq_i32 s1, 0x200
	s_waitcnt lgkmcnt(1)
	v_mov_b32_e32 v100, v32
	v_add_co_u32_e32 v32, vcc, s2, v42
	s_waitcnt lgkmcnt(0)
	v_mov_b32_e32 v101, v28
	v_mov_b32_e32 v28, v33
	v_addc_co_u32_e32 v33, vcc, -1, v43, vcc
	v_mov_b32_e32 v102, v112
	v_add_u32_e32 v32, 0x10000, v87
	v_mov_b32_e32 v50, v34
	v_mov_b32_e32 v51, v30
	v_mov_b32_e32 v30, v35
	ds_read_b128 v[32:35], v32
	s_movk_i32 s2, 0xa000
	v_pk_fma_f32 v[62:63], v[102:103], v[62:63], v[60:61] op_sel_hi:[0,1,1]
	v_add_co_u32_e32 v60, vcc, s2, v42
	s_movk_i32 s2, 0xd000
	s_nop 0
	v_addc_co_u32_e32 v61, vcc, -1, v43, vcc
	v_pk_fma_f32 v[64:65], v[102:103], v[88:89], v[64:65] op_sel_hi:[0,1,1]
	v_add_co_u32_e32 v88, vcc, s2, v42
	v_pk_fma_f32 v[66:67], v[102:103], v[90:91], v[66:67] op_sel_hi:[0,1,1]
	s_waitcnt lgkmcnt(0)
	v_fmac_f32_e32 v86, v102, v32
	v_addc_co_u32_e32 v89, vcc, -1, v43, vcc
	v_mov_b32_e32 v90, v114
	s_nop 0
	v_mov_b32_e32 v60, v116
	v_mov_b32_e32 v32, v118
	v_pk_fma_f32 v[68:69], v[102:103], v[92:93], v[68:69] op_sel_hi:[0,1,1]
	v_pk_fma_f32 v[70:71], v[102:103], v[94:95], v[70:71] op_sel_hi:[0,1,1]
	v_pk_fma_f32 v[72:73], v[102:103], v[96:97], v[72:73] op_sel_hi:[0,1,1]
	v_pk_fma_f32 v[74:75], v[102:103], v[98:99], v[74:75] op_sel_hi:[0,1,1]
	v_pk_fma_f32 v[76:77], v[102:103], v[100:101], v[76:77] op_sel_hi:[0,1,1]
	s_mov_b64 s[2:3], 0xc000
	v_lshl_add_u64 v[42:43], v[42:43], 0, s[2:3]
	v_pk_fma_f32 v[62:63], v[90:91], v[0:1], v[62:63] op_sel_hi:[0,1,1]
	v_pk_fma_f32 v[64:65], v[90:91], v[4:5], v[64:65] op_sel_hi:[0,1,1]
	v_pk_fma_f32 v[66:67], v[90:91], v[8:9], v[66:67] op_sel_hi:[0,1,1]
	v_pk_fma_f32 v[68:69], v[90:91], v[12:13], v[68:69] op_sel_hi:[0,1,1]
	v_pk_fma_f32 v[0:1], v[90:91], v[16:17], v[70:71] op_sel_hi:[0,1,1]
	v_pk_fma_f32 v[4:5], v[90:91], v[20:21], v[72:73] op_sel_hi:[0,1,1]
	v_pk_fma_f32 v[8:9], v[90:91], v[24:25], v[74:75] op_sel_hi:[0,1,1]
	v_pk_fma_f32 v[12:13], v[90:91], v[28:29], v[76:77] op_sel_hi:[0,1,1]
	v_fmac_f32_e32 v86, v90, v33
	v_pk_fma_f32 v[16:17], v[60:61], v[52:53], v[62:63] op_sel_hi:[0,1,1]
	v_pk_fma_f32 v[20:21], v[60:61], v[54:55], v[64:65] op_sel_hi:[0,1,1]
	v_pk_fma_f32 v[24:25], v[60:61], v[56:57], v[66:67] op_sel_hi:[0,1,1]
	v_pk_fma_f32 v[28:29], v[60:61], v[58:59], v[68:69] op_sel_hi:[0,1,1]
	v_pk_fma_f32 v[0:1], v[60:61], v[44:45], v[0:1] op_sel_hi:[0,1,1]
	v_pk_fma_f32 v[4:5], v[60:61], v[46:47], v[4:5] op_sel_hi:[0,1,1]
	v_pk_fma_f32 v[8:9], v[60:61], v[48:49], v[8:9] op_sel_hi:[0,1,1]
	v_pk_fma_f32 v[12:13], v[60:61], v[50:51], v[12:13] op_sel_hi:[0,1,1]
	v_fmac_f32_e32 v86, v60, v34
	v_pk_fma_f32 v[60:61], v[32:33], v[2:3], v[16:17] op_sel_hi:[0,1,1]
	v_pk_fma_f32 v[64:65], v[32:33], v[6:7], v[20:21] op_sel_hi:[0,1,1]
	v_pk_fma_f32 v[66:67], v[32:33], v[10:11], v[24:25] op_sel_hi:[0,1,1]
	v_pk_fma_f32 v[68:69], v[32:33], v[14:15], v[28:29] op_sel_hi:[0,1,1]
	v_pk_fma_f32 v[70:71], v[32:33], v[18:19], v[0:1] op_sel_hi:[0,1,1]
	v_pk_fma_f32 v[72:73], v[32:33], v[22:23], v[4:5] op_sel_hi:[0,1,1]
	v_pk_fma_f32 v[74:75], v[32:33], v[26:27], v[8:9] op_sel_hi:[0,1,1]
	v_pk_fma_f32 v[76:77], v[32:33], v[30:31], v[12:13] op_sel_hi:[0,1,1]
	v_fmac_f32_e32 v86, v32, v35
	s_cbranch_scc0 .LBB0_840
	ds_write2st64_b32 v37, v60, v61 offset1:1
	ds_write2st64_b32 v37, v64, v65 offset0:2 offset1:3
	ds_write2st64_b32 v37, v66, v67 offset0:4 offset1:5
	ds_write2st64_b32 v37, v68, v69 offset0:6 offset1:7
	ds_write2st64_b32 v37, v70, v71 offset0:8 offset1:9
	ds_write2st64_b32 v37, v72, v73 offset0:10 offset1:11
	ds_write2st64_b32 v37, v74, v75 offset0:12 offset1:13
	ds_write2st64_b32 v37, v76, v77 offset0:14 offset1:15
	ds_write_b32 v37, v86 offset:4096
	s_waitcnt lgkmcnt(0)
	s_barrier
	s_and_saveexec_b64 s[2:3], s[42:43]
	v_readlane_b32 s50, v253, 61
	v_readlane_b32 s51, v253, 62
	s_cbranch_execz .LBB0_825
	s_mul_i32 s1, s44, 0xc00
	s_add_i32 s1, s1, s0
	v_or_b32_e32 v0, s1, v80
	v_readlane_b32 s4, v255, 4
	v_ashrrev_i32_e32 v1, 31, v0
	v_readlane_b32 s5, v255, 5
	v_readlane_b32 s6, v255, 6
	v_readlane_b32 s8, v255, 8
	v_readlane_b32 s9, v255, 9
	v_readlane_b32 s16, v255, 16
	v_readlane_b32 s17, v255, 17
	v_readlane_b32 s18, v255, 18
	v_readlane_b32 s19, v255, 19
	s_mul_i32 s44, s44, 17
	s_mov_b64 s[8:9], 0x800
	s_movk_i32 s6, 0x204
	s_brev_b32 s5, 1
	s_movk_i32 s19, 0xff
	s_movk_i32 s18, 0x1f8
	v_lshl_add_u64 v[0:1], v[0:1], 2, s[16:17]
	v_readlane_b32 s17, v255, 35
	s_mov_b32 s16, 0x1ffffe0
	v_or_b32_e32 v2, s0, v80
	s_mov_b64 s[0:1], 0
	v_mov_b32_e32 v3, v36
	v_readlane_b32 s7, v255, 7
	v_readlane_b32 s10, v255, 10
	v_readlane_b32 s11, v255, 11
	v_readlane_b32 s12, v255, 12
	v_readlane_b32 s13, v255, 13
	v_readlane_b32 s14, v255, 14
	v_readlane_b32 s15, v255, 15
